# v11 + 8 bytes of s_nop padding after the in-proj phase (code placement of the attention / out-proj code)
# speedup vs baseline: 1.0480x; 1.0023x over previous
; #define PG8_WAIT_V(n) asm volatile("s_waitcnt vmcnt(" #n ")" ::: "memory")
; #define PG8_BAR __builtin_amdgcn_s_barrier()
; template <class Epi, class Sched, bool ALIGN_EPI = false, bool SP2 = false>
; __device__ __forceinline__ void gemm_phase(PG8_LAS unsigned char* lds, const Gemm g, const Sched& S, const Epi& E) {
;     ...
;     PG8_WAIT_V(0);
;     if constexpr (!ALIGN_EPI) { if (wr == 0) PG8_BAR; }
;     PG8_BAR;
.LBB0_340:
	s_nop 0
	s_nop 0
	s_waitcnt vmcnt(0)
	s_barrier
